# EpiResid epilogue prologue: the 4 serialized gate/scale/gain load ladders merged into one batch issued before the x loads, single counted wait
# baseline (speedup 1.0000x reference)
;     __device__ __forceinline__ void operator()(const f32x4 (&acc)[2][2][4][2], const Unit& u, int wr, int wc, int fr, int fq) const {
;     ...
;         const size_t rowb = (size_t)u.pm * BM + wr * 64 + fr; const int col0 = u.pn * BM + wc * 32 + 4 * fq; const float* gb = gmod + (size_t)(u.pm >> 4) * 6144;
;         f32x4 gv[2][2], Gv[2][2];
; #pragma unroll
;         for (int bj = 0; bj < 2; ++bj)
; #pragma unroll
;             for (int n = 0; n < 2; ++n) { gv[bj][n] = *(const f32x4*)(gb + col0 + bj * HALF + n * 16);
;                 if (XG) Gv[bj][n] = *(const f32x4*)(gnorm + col0 + bj * HALF + n * 16) * (1.0f + *(const f32x4*)(scmod + (size_t)(u.pm >> 4) * 6144 + col0 + bj * HALF + n * 16)); }
.LBB0_63:
	v_mov_b32_e32 v185, v221
	s_lshl_b32 s35, s42, 8
	v_bfe_u32 v184, v185, 4, 2
	v_lshl_or_b32 v0, v184, 2, s35
	s_ashr_i32 s35, s44, 4
	v_or_b32_e32 v164, s65, v0
	s_mul_hi_i32 s39, s35, 0x6000
	s_mulk_i32 s35, 0x6000
	s_add_u32 s42, s61, s35
	v_ashrrev_i32_e32 v165, 31, v164
	s_addc_u32 s43, s62, s39
	v_lshlrev_b64 v[46:47], 2, v[164:165]
	v_lshl_add_u64 v[44:45], s[42:43], 0, v[46:47]
	global_load_dwordx4 v[52:55], v[44:45], off
	s_add_u32 s42, s30, s35
	s_addc_u32 s43, s63, s39
	v_cndmask_b32_e64 v0, 0, 1, s[18:19]
	v_lshl_add_u64 v[2:3], s[12:13], 0, v[46:47]
	v_lshl_add_u64 v[174:175], s[42:43], 0, v[46:47]
	v_cmp_ne_u32_e64 s[42:43], 1, v0
	s_andn2_b64 vcc, exec, s[18:19]
	global_load_dwordx4 v[56:59], v[44:45], off offset:64
	global_load_dwordx4 v[48:51], v[44:45], off offset:512
	s_movk_i32 s87, 0x200
	s_mov_b64 s[88:89], 0x800
	s_cbranch_vccnz .Lpro_out_g3
	global_load_dwordx4 v[208:211], v[174:175], off
	global_load_dwordx4 v[170:173], v[2:3], off
	global_load_dwordx4 v[212:215], v[174:175], off offset:64
	global_load_dwordx4 v[166:169], v[2:3], off offset:64
	global_load_dwordx4 v[216:219], v[174:175], off offset:512
	global_load_dwordx4 v[160:163], v[2:3], off offset:512
	global_load_dwordx4 v[176:179], v[174:175], off offset:576
	global_load_dwordx4 v[156:159], v[2:3], off offset:576

; __device__ __forceinline__ unsigned cvt_pk_bf16(float lo, float hi) { unsigned r; asm volatile("v_cvt_pk_bf16_f32 %0, %1, %2" : "=v"(r) : "v"(lo), "v"(hi)); return r; }
;     __device__ __forceinline__ void operator()(const f32x4 (&acc)[2][2][4][2], const Unit& u, int wr, int wc, int fr, int fq) const {
;     ...
;             for (int n = 0; n < 2; ++n) { gv[bj][n] = *(const f32x4*)(gb + col0 + bj * HALF + n * 16);
;                 if (XG) Gv[bj][n] = *(const f32x4*)(gnorm + col0 + bj * HALF + n * 16) * (1.0f + *(const f32x4*)(scmod + (size_t)(u.pm >> 4) * 6144 + col0 + bj * HALF + n * 16)); }
; #pragma unroll
;         for (int ai = 0; ai < 2; ++ai)
; #pragma unroll
;             for (int m = 0; m < 4; ++m) { const size_t row = rowb + ai * HALF + m * 16; const size_t off = row * 1024 + col0; float s = 0.f;
; #pragma unroll
;                 for (int bj = 0; bj < 2; ++bj) { u32x2 w[2];
; #pragma unroll
;                     for (int n = 0; n < 2; ++n) { const f32x4 xv = *(const __attribute__((address_space(1))) f32x4*)(xin + off + bj * HALF + n * 16);
;                         const f32x4 xn = xv + gv[bj][n] * acc[ai][bj][m][n];
;                         *(__attribute__((address_space(1))) f32x4*)(out + off + bj * HALF + n * 16) = xn;
;                         if (XG) { s += (xn[0] * xn[0] + xn[1] * xn[1]) + (xn[2] * xn[2] + xn[3] * xn[3]); const f32x4 t = xn * Gv[bj][n];
;                             w[n].x = cvt_pk_bf16(t[0], t[1]); w[n].y = cvt_pk_bf16(t[2], t[3]); } }
;                     if (XG) {
;                         const bool odd = (fq & 1) != 0; const u32x2 snd = odd ? w[0] : w[1]; u32x2 rcv; rcv.x = __shfl_xor(snd.x, 16); rcv.y = __shfl_xor(snd.y, 16);
;                         u32x4 o4; if (odd) { o4.x = rcv.x; o4.y = rcv.y; o4.z = w[1].x; o4.w = w[1].y; } else { o4.x = w[0].x; o4.y = w[0].y; o4.z = rcv.x; o4.w = rcv.y; }
;                         *(u32x4*)(XG + off + bj * HALF + (odd ? 12 : 0)) = o4; } }
;                 if (XG) { s += __shfl_xor(s, 16); s += __shfl_xor(s, 32); if (fq == 0) atomicAdd(ssq + row, s); } }
.LBB0_71:
	s_ashr_i32 s45, s44, 31
	s_lshl_b64 s[44:45], s[44:45], 8
	s_add_u32 s35, s44, s64
	s_addc_u32 s39, s45, s68
	v_and_or_b32 v174, v185, 15, s35
	v_mov_b32_e32 v175, s39
	s_and_b64 vcc, exec, s[42:43]
	s_cbranch_vccnz .Lepi_out_orig
	v_lshlrev_b32_e32 v164, 2, v164
	v_lshl_add_u32 v164, v174, 12, v164
	v_bfe_u32 v0, v185, 4, 1
	v_lshrrev_b32_e32 v165, 1, v164
	v_mad_u32_u24 v165, v0, 24, v165
	v_mov_b32_e32 v175, v164
	v_mov_b32_e32 v2, 0
	v_mov_b32_e32 v3, 0
	global_load_dwordx4 v[184:187], v175, s[2:3] offset:0
	global_load_dwordx4 v[188:191], v175, s[2:3] offset:64
	global_load_dwordx4 v[192:195], v175, s[2:3] offset:512
	global_load_dwordx4 v[196:199], v175, s[2:3] offset:576
	v_add_u32_e32 v175, 0x10000, v175
	global_load_dwordx4 v[200:203], v175, s[2:3] offset:0
	global_load_dwordx4 v[204:207], v175, s[2:3] offset:64
	global_load_dwordx4 v[236:239], v175, s[2:3] offset:512
	global_load_dwordx4 v[240:243], v175, s[2:3] offset:576
	v_add_u32_e32 v175, 0x10000, v175
	global_load_dwordx4 v[244:247], v175, s[2:3] offset:0
	global_load_dwordx4 v[248:251], v175, s[2:3] offset:64
	s_waitcnt vmcnt(10)
	v_pk_add_f32 v[208:209], v[208:209], 1.0 op_sel_hi:[1,0]
	v_pk_add_f32 v[210:211], v[210:211], 1.0 op_sel_hi:[1,0]
	v_pk_add_f32 v[212:213], v[212:213], 1.0 op_sel_hi:[1,0]
	v_pk_add_f32 v[214:215], v[214:215], 1.0 op_sel_hi:[1,0]
	v_pk_add_f32 v[216:217], v[216:217], 1.0 op_sel_hi:[1,0]
	v_pk_add_f32 v[218:219], v[218:219], 1.0 op_sel_hi:[1,0]
	v_pk_add_f32 v[176:177], v[176:177], 1.0 op_sel_hi:[1,0]
	v_pk_add_f32 v[178:179], v[178:179], 1.0 op_sel_hi:[1,0]
	v_pk_mul_f32 v[170:171], v[170:171], v[208:209]
	v_pk_mul_f32 v[172:173], v[172:173], v[210:211]
	v_pk_mul_f32 v[166:167], v[166:167], v[212:213]
	v_pk_mul_f32 v[168:169], v[168:169], v[214:215]
	v_pk_mul_f32 v[160:161], v[160:161], v[216:217]
	v_pk_mul_f32 v[162:163], v[162:163], v[218:219]
	v_pk_mul_f32 v[156:157], v[156:157], v[176:177]
	v_pk_mul_f32 v[158:159], v[158:159], v[178:179]
	s_waitcnt vmcnt(8)
	v_pk_fma_f32 v[184:185], v[144:145], v[52:53], v[184:185]
	v_pk_fma_f32 v[186:187], v[146:147], v[54:55], v[186:187]
	v_pk_fma_f32 v[188:189], v[140:141], v[56:57], v[188:189]
	v_pk_fma_f32 v[190:191], v[142:143], v[58:59], v[190:191]
	global_store_dwordx4 v164, v[184:187], s[6:7] offset:0
	global_store_dwordx4 v164, v[188:191], s[6:7] offset:64
	global_load_dwordx4 v[144:147], v175, s[2:3] offset:512
	global_load_dwordx4 v[140:143], v175, s[2:3] offset:576
	v_add_u32_e32 v175, 0x10000, v175
	v_pk_fma_f32 v[2:3], v[184:185], v[184:185], v[2:3]
	v_pk_fma_f32 v[2:3], v[186:187], v[186:187], v[2:3]
	v_pk_fma_f32 v[2:3], v[188:189], v[188:189], v[2:3]
	v_pk_fma_f32 v[2:3], v[190:191], v[190:191], v[2:3]
	v_pk_mul_f32 v[252:253], v[184:185], v[170:171]
	v_cvt_pk_bf16_f32 v176, v252, v253
	v_pk_mul_f32 v[252:253], v[186:187], v[172:173]
	v_cvt_pk_bf16_f32 v177, v252, v253
	v_pk_mul_f32 v[252:253], v[188:189], v[166:167]
	v_cvt_pk_bf16_f32 v178, v252, v253
	v_pk_mul_f32 v[252:253], v[190:191], v[168:169]
	v_cvt_pk_bf16_f32 v179, v252, v253
	s_nop 1
	v_permlane16_swap_b32_e32 v176, v178
	v_permlane16_swap_b32_e32 v177, v179
	global_store_dwordx4 v165, v[176:179], s[10:11] offset:0
	s_waitcnt vmcnt(11)
	v_pk_fma_f32 v[192:193], v[136:137], v[48:49], v[192:193]
	v_pk_fma_f32 v[194:195], v[138:139], v[50:51], v[194:195]
	v_pk_fma_f32 v[196:197], v[132:133], v[44:45], v[196:197]
	v_pk_fma_f32 v[198:199], v[134:135], v[46:47], v[198:199]
	global_store_dwordx4 v164, v[192:195], s[6:7] offset:512
	global_store_dwordx4 v164, v[196:199], s[6:7] offset:576
	global_load_dwordx4 v[136:139], v175, s[2:3] offset:0
	global_load_dwordx4 v[132:135], v175, s[2:3] offset:64
	v_pk_fma_f32 v[2:3], v[192:193], v[192:193], v[2:3]
	v_pk_fma_f32 v[2:3], v[194:195], v[194:195], v[2:3]
	v_pk_fma_f32 v[2:3], v[196:197], v[196:197], v[2:3]
	v_pk_fma_f32 v[2:3], v[198:199], v[198:199], v[2:3]
	v_pk_mul_f32 v[252:253], v[192:193], v[160:161]
	v_cvt_pk_bf16_f32 v176, v252, v253
	v_pk_mul_f32 v[252:253], v[194:195], v[162:163]
	v_cvt_pk_bf16_f32 v177, v252, v253
	v_pk_mul_f32 v[252:253], v[196:197], v[156:157]
	v_cvt_pk_bf16_f32 v178, v252, v253
	v_pk_mul_f32 v[252:253], v[198:199], v[158:159]
	v_cvt_pk_bf16_f32 v179, v252, v253
	s_nop 1
	v_permlane16_swap_b32_e32 v176, v178
	v_permlane16_swap_b32_e32 v177, v179
	global_store_dwordx4 v165, v[176:179], s[10:11] offset:256
	v_add_f32_e32 v2, v2, v3
	v_mov_b32_e32 v0, v2
	s_nop 1
	v_permlane16_swap_b32_e32 v2, v0
	v_add_f32_e32 v2, v2, v0
	v_mov_b32_e32 v0, v2
	s_nop 1
	v_permlane32_swap_b32_e32 v2, v0
	v_add_f32_e32 v2, v2, v0
	v_lshrrev_b32_e32 v252, 12, v164
	v_lshlrev_b32_e32 v252, 2, v252
	s_mov_b64 exec, 0xffff
	global_atomic_add_f32 v252, v2, s[14:15]
	s_mov_b64 exec, -1
	v_add_u32_e32 v164, 0x10000, v164
	v_add_u32_e32 v165, 0x8000, v165
	v_mov_b32_e32 v2, 0
	v_mov_b32_e32 v3, 0
	s_waitcnt vmcnt(15)
	v_pk_fma_f32 v[200:201], v[128:129], v[52:53], v[200:201]
	v_pk_fma_f32 v[202:203], v[130:131], v[54:55], v[202:203]
	v_pk_fma_f32 v[204:205], v[124:125], v[56:57], v[204:205]
	v_pk_fma_f32 v[206:207], v[126:127], v[58:59], v[206:207]
	global_store_dwordx4 v164, v[200:203], s[6:7] offset:0
	global_store_dwordx4 v164, v[204:207], s[6:7] offset:64
	global_load_dwordx4 v[128:131], v175, s[2:3] offset:512
	global_load_dwordx4 v[124:127], v175, s[2:3] offset:576
	v_add_u32_e32 v175, 0x50000, v175
	v_pk_fma_f32 v[2:3], v[200:201], v[200:201], v[2:3]
	v_pk_fma_f32 v[2:3], v[202:203], v[202:203], v[2:3]
	v_pk_fma_f32 v[2:3], v[204:205], v[204:205], v[2:3]
	v_pk_fma_f32 v[2:3], v[206:207], v[206:207], v[2:3]
	v_pk_mul_f32 v[252:253], v[200:201], v[170:171]
	v_cvt_pk_bf16_f32 v176, v252, v253
	v_pk_mul_f32 v[252:253], v[202:203], v[172:173]
	v_cvt_pk_bf16_f32 v177, v252, v253
	v_pk_mul_f32 v[252:253], v[204:205], v[166:167]
	v_cvt_pk_bf16_f32 v178, v252, v253
	v_pk_mul_f32 v[252:253], v[206:207], v[168:169]
	v_cvt_pk_bf16_f32 v179, v252, v253
	s_nop 1
	v_permlane16_swap_b32_e32 v176, v178
	v_permlane16_swap_b32_e32 v177, v179
	global_store_dwordx4 v165, v[176:179], s[10:11] offset:0
	s_waitcnt vmcnt(18)
; __device__ __forceinline__ unsigned cvt_pk_bf16(float lo, float hi) { unsigned r; asm volatile("v_cvt_pk_bf16_f32 %0, %1, %2" : "=v"(r) : "v"(lo), "v"(hi)); return r; }
;     __device__ __forceinline__ void operator()(const f32x4 (&acc)[2][2][4][2], const Unit& u, int wr, int wc, int fr, int fq) const {
;     ...
;             for (int m = 0; m < 4; ++m) { const size_t row = rowb + ai * HALF + m * 16; const size_t off = row * 1024 + col0; float s = 0.f;
; #pragma unroll
;                 for (int bj = 0; bj < 2; ++bj) { u32x2 w[2];
; #pragma unroll
;                     for (int n = 0; n < 2; ++n) { const f32x4 xv = *(const __attribute__((address_space(1))) f32x4*)(xin + off + bj * HALF + n * 16);
;                         const f32x4 xn = xv + gv[bj][n] * acc[ai][bj][m][n];
;                         *(__attribute__((address_space(1))) f32x4*)(out + off + bj * HALF + n * 16) = xn;
;                         if (XG) { s += (xn[0] * xn[0] + xn[1] * xn[1]) + (xn[2] * xn[2] + xn[3] * xn[3]); const f32x4 t = xn * Gv[bj][n];
;                             w[n].x = cvt_pk_bf16(t[0], t[1]); w[n].y = cvt_pk_bf16(t[2], t[3]); } }
;                     if (XG) {
;                         const bool odd = (fq & 1) != 0; const u32x2 snd = odd ? w[0] : w[1]; u32x2 rcv; rcv.x = __shfl_xor(snd.x, 16); rcv.y = __shfl_xor(snd.y, 16);
;                         u32x4 o4; if (odd) { o4.x = rcv.x; o4.y = rcv.y; o4.z = w[1].x; o4.w = w[1].y; } else { o4.x = w[0].x; o4.y = w[0].y; o4.z = rcv.x; o4.w = rcv.y; }
;                         *(u32x4*)(XG + off + bj * HALF + (odd ? 12 : 0)) = o4; } }
;                 if (XG) { s += __shfl_xor(s, 16); s += __shfl_xor(s, 32); if (fq == 0) atomicAdd(ssq + row, s); } }
	v_pk_fma_f32 v[236:237], v[120:121], v[48:49], v[236:237]
	v_pk_fma_f32 v[238:239], v[122:123], v[50:51], v[238:239]
	v_pk_fma_f32 v[240:241], v[116:117], v[44:45], v[240:241]
	v_pk_fma_f32 v[242:243], v[118:119], v[46:47], v[242:243]
	global_store_dwordx4 v164, v[236:239], s[6:7] offset:512
	global_store_dwordx4 v164, v[240:243], s[6:7] offset:576
	global_load_dwordx4 v[120:123], v175, s[2:3] offset:0
	global_load_dwordx4 v[116:119], v175, s[2:3] offset:64
	v_pk_fma_f32 v[2:3], v[236:237], v[236:237], v[2:3]
	v_pk_fma_f32 v[2:3], v[238:239], v[238:239], v[2:3]
	v_pk_fma_f32 v[2:3], v[240:241], v[240:241], v[2:3]
	v_pk_fma_f32 v[2:3], v[242:243], v[242:243], v[2:3]
	v_pk_mul_f32 v[252:253], v[236:237], v[160:161]
	v_cvt_pk_bf16_f32 v176, v252, v253
	v_pk_mul_f32 v[252:253], v[238:239], v[162:163]
	v_cvt_pk_bf16_f32 v177, v252, v253
	v_pk_mul_f32 v[252:253], v[240:241], v[156:157]
	v_cvt_pk_bf16_f32 v178, v252, v253
	v_pk_mul_f32 v[252:253], v[242:243], v[158:159]
	v_cvt_pk_bf16_f32 v179, v252, v253
	s_nop 1
	v_permlane16_swap_b32_e32 v176, v178
	v_permlane16_swap_b32_e32 v177, v179
	global_store_dwordx4 v165, v[176:179], s[10:11] offset:256
	v_add_f32_e32 v2, v2, v3
	v_mov_b32_e32 v0, v2
	s_nop 1
	v_permlane16_swap_b32_e32 v2, v0
	v_add_f32_e32 v2, v2, v0
	v_mov_b32_e32 v0, v2
	s_nop 1
	v_permlane32_swap_b32_e32 v2, v0
	v_add_f32_e32 v2, v2, v0
	v_lshrrev_b32_e32 v252, 12, v164
	v_lshlrev_b32_e32 v252, 2, v252
	s_mov_b64 exec, 0xffff
	global_atomic_add_f32 v252, v2, s[14:15]
	s_mov_b64 exec, -1
	v_add_u32_e32 v164, 0x10000, v164
	v_add_u32_e32 v165, 0x8000, v165
	v_mov_b32_e32 v2, 0
	v_mov_b32_e32 v3, 0
	s_waitcnt vmcnt(22)
	v_pk_fma_f32 v[244:245], v[112:113], v[52:53], v[244:245]
	v_pk_fma_f32 v[246:247], v[114:115], v[54:55], v[246:247]
	v_pk_fma_f32 v[248:249], v[108:109], v[56:57], v[248:249]
	v_pk_fma_f32 v[250:251], v[110:111], v[58:59], v[250:251]
	global_store_dwordx4 v164, v[244:247], s[6:7] offset:0
	global_store_dwordx4 v164, v[248:251], s[6:7] offset:64
	global_load_dwordx4 v[112:115], v175, s[2:3] offset:512
	global_load_dwordx4 v[108:111], v175, s[2:3] offset:576
	v_add_u32_e32 v175, 0x10000, v175
	v_pk_fma_f32 v[2:3], v[244:245], v[244:245], v[2:3]
	v_pk_fma_f32 v[2:3], v[246:247], v[246:247], v[2:3]
	v_pk_fma_f32 v[2:3], v[248:249], v[248:249], v[2:3]
	v_pk_fma_f32 v[2:3], v[250:251], v[250:251], v[2:3]
	v_pk_mul_f32 v[252:253], v[244:245], v[170:171]
	v_cvt_pk_bf16_f32 v176, v252, v253
	v_pk_mul_f32 v[252:253], v[246:247], v[172:173]
	v_cvt_pk_bf16_f32 v177, v252, v253
	v_pk_mul_f32 v[252:253], v[248:249], v[166:167]
	v_cvt_pk_bf16_f32 v178, v252, v253
	v_pk_mul_f32 v[252:253], v[250:251], v[168:169]
	v_cvt_pk_bf16_f32 v179, v252, v253
	s_nop 1
	v_permlane16_swap_b32_e32 v176, v178
	v_permlane16_swap_b32_e32 v177, v179
	global_store_dwordx4 v165, v[176:179], s[10:11] offset:0
	s_waitcnt vmcnt(23)
	v_pk_fma_f32 v[144:145], v[104:105], v[48:49], v[144:145]
	v_pk_fma_f32 v[146:147], v[106:107], v[50:51], v[146:147]
	v_pk_fma_f32 v[140:141], v[100:101], v[44:45], v[140:141]
	v_pk_fma_f32 v[142:143], v[102:103], v[46:47], v[142:143]
	global_store_dwordx4 v164, v[144:147], s[6:7] offset:512
	global_store_dwordx4 v164, v[140:143], s[6:7] offset:576
	global_load_dwordx4 v[104:107], v175, s[2:3] offset:0
	global_load_dwordx4 v[100:103], v175, s[2:3] offset:64
	v_pk_fma_f32 v[2:3], v[144:145], v[144:145], v[2:3]
	v_pk_fma_f32 v[2:3], v[146:147], v[146:147], v[2:3]
	v_pk_fma_f32 v[2:3], v[140:141], v[140:141], v[2:3]
	v_pk_fma_f32 v[2:3], v[142:143], v[142:143], v[2:3]
	v_pk_mul_f32 v[252:253], v[144:145], v[160:161]
	v_cvt_pk_bf16_f32 v176, v252, v253
	v_pk_mul_f32 v[252:253], v[146:147], v[162:163]
	v_cvt_pk_bf16_f32 v177, v252, v253
	v_pk_mul_f32 v[252:253], v[140:141], v[156:157]
	v_cvt_pk_bf16_f32 v178, v252, v253
	v_pk_mul_f32 v[252:253], v[142:143], v[158:159]
	v_cvt_pk_bf16_f32 v179, v252, v253
	s_nop 1
	v_permlane16_swap_b32_e32 v176, v178
	v_permlane16_swap_b32_e32 v177, v179
	global_store_dwordx4 v165, v[176:179], s[10:11] offset:256
	v_add_f32_e32 v2, v2, v3
	v_mov_b32_e32 v0, v2
	s_nop 1
	v_permlane16_swap_b32_e32 v2, v0
	v_add_f32_e32 v2, v2, v0
	v_mov_b32_e32 v0, v2
	s_nop 1
	v_permlane32_swap_b32_e32 v2, v0
	v_add_f32_e32 v2, v2, v0
	v_lshrrev_b32_e32 v252, 12, v164
	v_lshlrev_b32_e32 v252, 2, v252
	s_mov_b64 exec, 0xffff
	global_atomic_add_f32 v252, v2, s[14:15]
	s_mov_b64 exec, -1
	v_add_u32_e32 v164, 0x10000, v164
	v_add_u32_e32 v165, 0x8000, v165
	v_mov_b32_e32 v2, 0
	v_mov_b32_e32 v3, 0
	s_waitcnt vmcnt(24)
	v_pk_fma_f32 v[136:137], v[96:97], v[52:53], v[136:137]
	v_pk_fma_f32 v[138:139], v[98:99], v[54:55], v[138:139]
	v_pk_fma_f32 v[132:133], v[92:93], v[56:57], v[132:133]
	v_pk_fma_f32 v[134:135], v[94:95], v[58:59], v[134:135]
	global_store_dwordx4 v164, v[136:139], s[6:7] offset:0
	global_store_dwordx4 v164, v[132:135], s[6:7] offset:64
	global_load_dwordx4 v[96:99], v175, s[2:3] offset:512
	global_load_dwordx4 v[92:95], v175, s[2:3] offset:576
	v_add_u32_e32 v175, 0x10000, v175
	v_pk_fma_f32 v[2:3], v[136:137], v[136:137], v[2:3]
	v_pk_fma_f32 v[2:3], v[138:139], v[138:139], v[2:3]
	v_pk_fma_f32 v[2:3], v[132:133], v[132:133], v[2:3]
	v_pk_fma_f32 v[2:3], v[134:135], v[134:135], v[2:3]
	v_pk_mul_f32 v[252:253], v[136:137], v[170:171]
	v_cvt_pk_bf16_f32 v176, v252, v253
	v_pk_mul_f32 v[252:253], v[138:139], v[172:173]
	v_cvt_pk_bf16_f32 v177, v252, v253
	v_pk_mul_f32 v[252:253], v[132:133], v[166:167]
	v_cvt_pk_bf16_f32 v178, v252, v253
	v_pk_mul_f32 v[252:253], v[134:135], v[168:169]
	v_cvt_pk_bf16_f32 v179, v252, v253
	s_nop 1
	v_permlane16_swap_b32_e32 v176, v178
	v_permlane16_swap_b32_e32 v177, v179
	global_store_dwordx4 v165, v[176:179], s[10:11] offset:0
	s_waitcnt vmcnt(23)
; __device__ __forceinline__ unsigned cvt_pk_bf16(float lo, float hi) { unsigned r; asm volatile("v_cvt_pk_bf16_f32 %0, %1, %2" : "=v"(r) : "v"(lo), "v"(hi)); return r; }
;     __device__ __forceinline__ void operator()(const f32x4 (&acc)[2][2][4][2], const Unit& u, int wr, int wc, int fr, int fq) const {
;     ...
;             for (int m = 0; m < 4; ++m) { const size_t row = rowb + ai * HALF + m * 16; const size_t off = row * 1024 + col0; float s = 0.f;
; #pragma unroll
;                 for (int bj = 0; bj < 2; ++bj) { u32x2 w[2];
; #pragma unroll
;                     for (int n = 0; n < 2; ++n) { const f32x4 xv = *(const __attribute__((address_space(1))) f32x4*)(xin + off + bj * HALF + n * 16);
;                         const f32x4 xn = xv + gv[bj][n] * acc[ai][bj][m][n];
;                         *(__attribute__((address_space(1))) f32x4*)(out + off + bj * HALF + n * 16) = xn;
;                         if (XG) { s += (xn[0] * xn[0] + xn[1] * xn[1]) + (xn[2] * xn[2] + xn[3] * xn[3]); const f32x4 t = xn * Gv[bj][n];
;                             w[n].x = cvt_pk_bf16(t[0], t[1]); w[n].y = cvt_pk_bf16(t[2], t[3]); } }
;                     if (XG) {
;                         const bool odd = (fq & 1) != 0; const u32x2 snd = odd ? w[0] : w[1]; u32x2 rcv; rcv.x = __shfl_xor(snd.x, 16); rcv.y = __shfl_xor(snd.y, 16);
;                         u32x4 o4; if (odd) { o4.x = rcv.x; o4.y = rcv.y; o4.z = w[1].x; o4.w = w[1].y; } else { o4.x = w[0].x; o4.y = w[0].y; o4.z = rcv.x; o4.w = rcv.y; }
;                         *(u32x4*)(XG + off + bj * HALF + (odd ? 12 : 0)) = o4; } }
;                 if (XG) { s += __shfl_xor(s, 16); s += __shfl_xor(s, 32); if (fq == 0) atomicAdd(ssq + row, s); } }
	v_pk_fma_f32 v[128:129], v[88:89], v[48:49], v[128:129]
	v_pk_fma_f32 v[130:131], v[90:91], v[50:51], v[130:131]
	v_pk_fma_f32 v[124:125], v[84:85], v[44:45], v[124:125]
	v_pk_fma_f32 v[126:127], v[86:87], v[46:47], v[126:127]
	global_store_dwordx4 v164, v[128:131], s[6:7] offset:512
	global_store_dwordx4 v164, v[124:127], s[6:7] offset:576
	global_load_dwordx4 v[88:91], v175, s[2:3] offset:0
	global_load_dwordx4 v[84:87], v175, s[2:3] offset:64
	v_pk_fma_f32 v[2:3], v[128:129], v[128:129], v[2:3]
	v_pk_fma_f32 v[2:3], v[130:131], v[130:131], v[2:3]
	v_pk_fma_f32 v[2:3], v[124:125], v[124:125], v[2:3]
	v_pk_fma_f32 v[2:3], v[126:127], v[126:127], v[2:3]
	v_pk_mul_f32 v[252:253], v[128:129], v[160:161]
	v_cvt_pk_bf16_f32 v176, v252, v253
	v_pk_mul_f32 v[252:253], v[130:131], v[162:163]
	v_cvt_pk_bf16_f32 v177, v252, v253
	v_pk_mul_f32 v[252:253], v[124:125], v[156:157]
	v_cvt_pk_bf16_f32 v178, v252, v253
	v_pk_mul_f32 v[252:253], v[126:127], v[158:159]
	v_cvt_pk_bf16_f32 v179, v252, v253
	s_nop 1
	v_permlane16_swap_b32_e32 v176, v178
	v_permlane16_swap_b32_e32 v177, v179
	global_store_dwordx4 v165, v[176:179], s[10:11] offset:256
	v_add_f32_e32 v2, v2, v3
	v_mov_b32_e32 v0, v2
	s_nop 1
	v_permlane16_swap_b32_e32 v2, v0
	v_add_f32_e32 v2, v2, v0
	v_mov_b32_e32 v0, v2
	s_nop 1
	v_permlane32_swap_b32_e32 v2, v0
	v_add_f32_e32 v2, v2, v0
	v_lshrrev_b32_e32 v252, 12, v164
	v_lshlrev_b32_e32 v252, 2, v252
	s_mov_b64 exec, 0xffff
	global_atomic_add_f32 v252, v2, s[14:15]
	s_mov_b64 exec, -1
	v_add_u32_e32 v164, 0x50000, v164
	v_add_u32_e32 v165, 0x28000, v165
	v_mov_b32_e32 v2, 0
	v_mov_b32_e32 v3, 0
	s_waitcnt vmcnt(24)
	v_pk_fma_f32 v[120:121], v[80:81], v[52:53], v[120:121]
	v_pk_fma_f32 v[122:123], v[82:83], v[54:55], v[122:123]
	v_pk_fma_f32 v[116:117], v[76:77], v[56:57], v[116:117]
	v_pk_fma_f32 v[118:119], v[78:79], v[58:59], v[118:119]
	global_store_dwordx4 v164, v[120:123], s[6:7] offset:0
	global_store_dwordx4 v164, v[116:119], s[6:7] offset:64
	global_load_dwordx4 v[80:83], v175, s[2:3] offset:512
	global_load_dwordx4 v[76:79], v175, s[2:3] offset:576
	v_add_u32_e32 v175, 0x10000, v175
	v_pk_fma_f32 v[2:3], v[120:121], v[120:121], v[2:3]
	v_pk_fma_f32 v[2:3], v[122:123], v[122:123], v[2:3]
	v_pk_fma_f32 v[2:3], v[116:117], v[116:117], v[2:3]
	v_pk_fma_f32 v[2:3], v[118:119], v[118:119], v[2:3]
	v_pk_mul_f32 v[252:253], v[120:121], v[170:171]
	v_cvt_pk_bf16_f32 v176, v252, v253
	v_pk_mul_f32 v[252:253], v[122:123], v[172:173]
	v_cvt_pk_bf16_f32 v177, v252, v253
	v_pk_mul_f32 v[252:253], v[116:117], v[166:167]
	v_cvt_pk_bf16_f32 v178, v252, v253
	v_pk_mul_f32 v[252:253], v[118:119], v[168:169]
	v_cvt_pk_bf16_f32 v179, v252, v253
	s_nop 1
	v_permlane16_swap_b32_e32 v176, v178
	v_permlane16_swap_b32_e32 v177, v179
	global_store_dwordx4 v165, v[176:179], s[10:11] offset:0
	s_waitcnt vmcnt(23)
	v_pk_fma_f32 v[112:113], v[72:73], v[48:49], v[112:113]
	v_pk_fma_f32 v[114:115], v[74:75], v[50:51], v[114:115]
	v_pk_fma_f32 v[108:109], v[68:69], v[44:45], v[108:109]
	v_pk_fma_f32 v[110:111], v[70:71], v[46:47], v[110:111]
	global_store_dwordx4 v164, v[112:115], s[6:7] offset:512
	global_store_dwordx4 v164, v[108:111], s[6:7] offset:576
	global_load_dwordx4 v[72:75], v175, s[2:3] offset:0
	global_load_dwordx4 v[68:71], v175, s[2:3] offset:64
	v_pk_fma_f32 v[2:3], v[112:113], v[112:113], v[2:3]
	v_pk_fma_f32 v[2:3], v[114:115], v[114:115], v[2:3]
	v_pk_fma_f32 v[2:3], v[108:109], v[108:109], v[2:3]
	v_pk_fma_f32 v[2:3], v[110:111], v[110:111], v[2:3]
	v_pk_mul_f32 v[252:253], v[112:113], v[160:161]
	v_cvt_pk_bf16_f32 v176, v252, v253
	v_pk_mul_f32 v[252:253], v[114:115], v[162:163]
	v_cvt_pk_bf16_f32 v177, v252, v253
	v_pk_mul_f32 v[252:253], v[108:109], v[156:157]
	v_cvt_pk_bf16_f32 v178, v252, v253
	v_pk_mul_f32 v[252:253], v[110:111], v[158:159]
	v_cvt_pk_bf16_f32 v179, v252, v253
	s_nop 1
	v_permlane16_swap_b32_e32 v176, v178
	v_permlane16_swap_b32_e32 v177, v179
	global_store_dwordx4 v165, v[176:179], s[10:11] offset:256
	v_add_f32_e32 v2, v2, v3
	v_mov_b32_e32 v0, v2
	s_nop 1
	v_permlane16_swap_b32_e32 v2, v0
	v_add_f32_e32 v2, v2, v0
	v_mov_b32_e32 v0, v2
	s_nop 1
	v_permlane32_swap_b32_e32 v2, v0
	v_add_f32_e32 v2, v2, v0
	v_lshrrev_b32_e32 v252, 12, v164
	v_lshlrev_b32_e32 v252, 2, v252
	s_mov_b64 exec, 0xffff
	global_atomic_add_f32 v252, v2, s[14:15]
	s_mov_b64 exec, -1
	v_add_u32_e32 v164, 0x10000, v164
	v_add_u32_e32 v165, 0x8000, v165
	v_mov_b32_e32 v2, 0
	v_mov_b32_e32 v3, 0
	s_waitcnt vmcnt(24)
	v_pk_fma_f32 v[104:105], v[64:65], v[52:53], v[104:105]
	v_pk_fma_f32 v[106:107], v[66:67], v[54:55], v[106:107]
	v_pk_fma_f32 v[100:101], v[60:61], v[56:57], v[100:101]
	v_pk_fma_f32 v[102:103], v[62:63], v[58:59], v[102:103]
	global_store_dwordx4 v164, v[104:107], s[6:7] offset:0
	global_store_dwordx4 v164, v[100:103], s[6:7] offset:64
	global_load_dwordx4 v[64:67], v175, s[2:3] offset:512
	global_load_dwordx4 v[60:63], v175, s[2:3] offset:576
	v_pk_fma_f32 v[2:3], v[104:105], v[104:105], v[2:3]
	v_pk_fma_f32 v[2:3], v[106:107], v[106:107], v[2:3]
	v_pk_fma_f32 v[2:3], v[100:101], v[100:101], v[2:3]
	v_pk_fma_f32 v[2:3], v[102:103], v[102:103], v[2:3]
	v_pk_mul_f32 v[252:253], v[104:105], v[170:171]
	v_cvt_pk_bf16_f32 v176, v252, v253
	v_pk_mul_f32 v[252:253], v[106:107], v[172:173]
	v_cvt_pk_bf16_f32 v177, v252, v253
	v_pk_mul_f32 v[252:253], v[100:101], v[166:167]
	v_cvt_pk_bf16_f32 v178, v252, v253
	v_pk_mul_f32 v[252:253], v[102:103], v[168:169]
	v_cvt_pk_bf16_f32 v179, v252, v253
	s_nop 1
	v_permlane16_swap_b32_e32 v176, v178
	v_permlane16_swap_b32_e32 v177, v179
	global_store_dwordx4 v165, v[176:179], s[10:11] offset:0
	s_waitcnt vmcnt(23)
; __device__ __forceinline__ unsigned cvt_pk_bf16(float lo, float hi) { unsigned r; asm volatile("v_cvt_pk_bf16_f32 %0, %1, %2" : "=v"(r) : "v"(lo), "v"(hi)); return r; }
;     __device__ __forceinline__ void operator()(const f32x4 (&acc)[2][2][4][2], const Unit& u, int wr, int wc, int fr, int fq) const {
;     ...
;             for (int m = 0; m < 4; ++m) { const size_t row = rowb + ai * HALF + m * 16; const size_t off = row * 1024 + col0; float s = 0.f;
; #pragma unroll
;                 for (int bj = 0; bj < 2; ++bj) { u32x2 w[2];
; #pragma unroll
;                     for (int n = 0; n < 2; ++n) { const f32x4 xv = *(const __attribute__((address_space(1))) f32x4*)(xin + off + bj * HALF + n * 16);
;                         const f32x4 xn = xv + gv[bj][n] * acc[ai][bj][m][n];
;                         *(__attribute__((address_space(1))) f32x4*)(out + off + bj * HALF + n * 16) = xn;
;                         if (XG) { s += (xn[0] * xn[0] + xn[1] * xn[1]) + (xn[2] * xn[2] + xn[3] * xn[3]); const f32x4 t = xn * Gv[bj][n];
;                             w[n].x = cvt_pk_bf16(t[0], t[1]); w[n].y = cvt_pk_bf16(t[2], t[3]); } }
;                     if (XG) {
;                         const bool odd = (fq & 1) != 0; const u32x2 snd = odd ? w[0] : w[1]; u32x2 rcv; rcv.x = __shfl_xor(snd.x, 16); rcv.y = __shfl_xor(snd.y, 16);
;                         u32x4 o4; if (odd) { o4.x = rcv.x; o4.y = rcv.y; o4.z = w[1].x; o4.w = w[1].y; } else { o4.x = w[0].x; o4.y = w[0].y; o4.z = rcv.x; o4.w = rcv.y; }
;                         *(u32x4*)(XG + off + bj * HALF + (odd ? 12 : 0)) = o4; } }
;                 if (XG) { s += __shfl_xor(s, 16); s += __shfl_xor(s, 32); if (fq == 0) atomicAdd(ssq + row, s); } }
	v_pk_fma_f32 v[96:97], v[40:41], v[48:49], v[96:97]
	v_pk_fma_f32 v[98:99], v[42:43], v[50:51], v[98:99]
	v_pk_fma_f32 v[92:93], v[36:37], v[44:45], v[92:93]
	v_pk_fma_f32 v[94:95], v[38:39], v[46:47], v[94:95]
	global_store_dwordx4 v164, v[96:99], s[6:7] offset:512
	global_store_dwordx4 v164, v[92:95], s[6:7] offset:576
	v_pk_fma_f32 v[2:3], v[96:97], v[96:97], v[2:3]
	v_pk_fma_f32 v[2:3], v[98:99], v[98:99], v[2:3]
	v_pk_fma_f32 v[2:3], v[92:93], v[92:93], v[2:3]
	v_pk_fma_f32 v[2:3], v[94:95], v[94:95], v[2:3]
	v_pk_mul_f32 v[252:253], v[96:97], v[160:161]
	v_cvt_pk_bf16_f32 v176, v252, v253
	v_pk_mul_f32 v[252:253], v[98:99], v[162:163]
	v_cvt_pk_bf16_f32 v177, v252, v253
	v_pk_mul_f32 v[252:253], v[92:93], v[156:157]
	v_cvt_pk_bf16_f32 v178, v252, v253
	v_pk_mul_f32 v[252:253], v[94:95], v[158:159]
	v_cvt_pk_bf16_f32 v179, v252, v253
	s_nop 1
	v_permlane16_swap_b32_e32 v176, v178
	v_permlane16_swap_b32_e32 v177, v179
	global_store_dwordx4 v165, v[176:179], s[10:11] offset:256
	v_add_f32_e32 v2, v2, v3
	v_mov_b32_e32 v0, v2
	s_nop 1
	v_permlane16_swap_b32_e32 v2, v0
	v_add_f32_e32 v2, v2, v0
	v_mov_b32_e32 v0, v2
	s_nop 1
	v_permlane32_swap_b32_e32 v2, v0
	v_add_f32_e32 v2, v2, v0
	v_lshrrev_b32_e32 v252, 12, v164
	v_lshlrev_b32_e32 v252, 2, v252
	s_mov_b64 exec, 0xffff
	global_atomic_add_f32 v252, v2, s[14:15]
	s_mov_b64 exec, -1
	v_add_u32_e32 v164, 0x10000, v164
	v_add_u32_e32 v165, 0x8000, v165
	v_mov_b32_e32 v2, 0
	v_mov_b32_e32 v3, 0
	s_waitcnt vmcnt(22)
	v_pk_fma_f32 v[88:89], v[32:33], v[52:53], v[88:89]
	v_pk_fma_f32 v[90:91], v[34:35], v[54:55], v[90:91]
	v_pk_fma_f32 v[84:85], v[28:29], v[56:57], v[84:85]
	v_pk_fma_f32 v[86:87], v[30:31], v[58:59], v[86:87]
	global_store_dwordx4 v164, v[88:91], s[6:7] offset:0
	global_store_dwordx4 v164, v[84:87], s[6:7] offset:64
	v_pk_fma_f32 v[2:3], v[88:89], v[88:89], v[2:3]
	v_pk_fma_f32 v[2:3], v[90:91], v[90:91], v[2:3]
	v_pk_fma_f32 v[2:3], v[84:85], v[84:85], v[2:3]
	v_pk_fma_f32 v[2:3], v[86:87], v[86:87], v[2:3]
	v_pk_mul_f32 v[252:253], v[88:89], v[170:171]
	v_cvt_pk_bf16_f32 v176, v252, v253
	v_pk_mul_f32 v[252:253], v[90:91], v[172:173]
	v_cvt_pk_bf16_f32 v177, v252, v253
	v_pk_mul_f32 v[252:253], v[84:85], v[166:167]
	v_cvt_pk_bf16_f32 v178, v252, v253
	v_pk_mul_f32 v[252:253], v[86:87], v[168:169]
	v_cvt_pk_bf16_f32 v179, v252, v253
	s_nop 1
	v_permlane16_swap_b32_e32 v176, v178
	v_permlane16_swap_b32_e32 v177, v179
	global_store_dwordx4 v165, v[176:179], s[10:11] offset:0
	s_waitcnt vmcnt(19)
	v_pk_fma_f32 v[80:81], v[24:25], v[48:49], v[80:81]
	v_pk_fma_f32 v[82:83], v[26:27], v[50:51], v[82:83]
	v_pk_fma_f32 v[76:77], v[20:21], v[44:45], v[76:77]
	v_pk_fma_f32 v[78:79], v[22:23], v[46:47], v[78:79]
	global_store_dwordx4 v164, v[80:83], s[6:7] offset:512
	global_store_dwordx4 v164, v[76:79], s[6:7] offset:576
	v_pk_fma_f32 v[2:3], v[80:81], v[80:81], v[2:3]
	v_pk_fma_f32 v[2:3], v[82:83], v[82:83], v[2:3]
	v_pk_fma_f32 v[2:3], v[76:77], v[76:77], v[2:3]
	v_pk_fma_f32 v[2:3], v[78:79], v[78:79], v[2:3]
	v_pk_mul_f32 v[252:253], v[80:81], v[160:161]
	v_cvt_pk_bf16_f32 v176, v252, v253
	v_pk_mul_f32 v[252:253], v[82:83], v[162:163]
	v_cvt_pk_bf16_f32 v177, v252, v253
	v_pk_mul_f32 v[252:253], v[76:77], v[156:157]
	v_cvt_pk_bf16_f32 v178, v252, v253
	v_pk_mul_f32 v[252:253], v[78:79], v[158:159]
	v_cvt_pk_bf16_f32 v179, v252, v253
	s_nop 1
	v_permlane16_swap_b32_e32 v176, v178
	v_permlane16_swap_b32_e32 v177, v179
	global_store_dwordx4 v165, v[176:179], s[10:11] offset:256
	v_add_f32_e32 v2, v2, v3
	v_mov_b32_e32 v0, v2
	s_nop 1
	v_permlane16_swap_b32_e32 v2, v0
	v_add_f32_e32 v2, v2, v0
	v_mov_b32_e32 v0, v2
	s_nop 1
	v_permlane32_swap_b32_e32 v2, v0
	v_add_f32_e32 v2, v2, v0
	v_lshrrev_b32_e32 v252, 12, v164
	v_lshlrev_b32_e32 v252, 2, v252
	s_mov_b64 exec, 0xffff
	global_atomic_add_f32 v252, v2, s[14:15]
	s_mov_b64 exec, -1
	v_add_u32_e32 v164, 0x10000, v164
	v_add_u32_e32 v165, 0x8000, v165
	v_mov_b32_e32 v2, 0
	v_mov_b32_e32 v3, 0
	s_waitcnt vmcnt(18)
	v_pk_fma_f32 v[72:73], v[16:17], v[52:53], v[72:73]
	v_pk_fma_f32 v[74:75], v[18:19], v[54:55], v[74:75]
	v_pk_fma_f32 v[68:69], v[12:13], v[56:57], v[68:69]
	v_pk_fma_f32 v[70:71], v[14:15], v[58:59], v[70:71]
	global_store_dwordx4 v164, v[72:75], s[6:7] offset:0
	global_store_dwordx4 v164, v[68:71], s[6:7] offset:64
	v_pk_fma_f32 v[2:3], v[72:73], v[72:73], v[2:3]
	v_pk_fma_f32 v[2:3], v[74:75], v[74:75], v[2:3]
	v_pk_fma_f32 v[2:3], v[68:69], v[68:69], v[2:3]
	v_pk_fma_f32 v[2:3], v[70:71], v[70:71], v[2:3]
	v_pk_mul_f32 v[252:253], v[72:73], v[170:171]
	v_cvt_pk_bf16_f32 v176, v252, v253
	v_pk_mul_f32 v[252:253], v[74:75], v[172:173]
	v_cvt_pk_bf16_f32 v177, v252, v253
	v_pk_mul_f32 v[252:253], v[68:69], v[166:167]
	v_cvt_pk_bf16_f32 v178, v252, v253
	v_pk_mul_f32 v[252:253], v[70:71], v[168:169]
	v_cvt_pk_bf16_f32 v179, v252, v253
	s_nop 1
	v_permlane16_swap_b32_e32 v176, v178
	v_permlane16_swap_b32_e32 v177, v179
	global_store_dwordx4 v165, v[176:179], s[10:11] offset:0
	s_waitcnt vmcnt(15)
	v_pk_fma_f32 v[64:65], v[8:9], v[48:49], v[64:65]
	v_pk_fma_f32 v[66:67], v[10:11], v[50:51], v[66:67]
	v_pk_fma_f32 v[60:61], v[4:5], v[44:45], v[60:61]
	v_pk_fma_f32 v[62:63], v[6:7], v[46:47], v[62:63]
	global_store_dwordx4 v164, v[64:67], s[6:7] offset:512
	global_store_dwordx4 v164, v[60:63], s[6:7] offset:576
	v_pk_fma_f32 v[2:3], v[64:65], v[64:65], v[2:3]
	v_pk_fma_f32 v[2:3], v[66:67], v[66:67], v[2:3]
	v_pk_fma_f32 v[2:3], v[60:61], v[60:61], v[2:3]
	v_pk_fma_f32 v[2:3], v[62:63], v[62:63], v[2:3]
	v_pk_mul_f32 v[252:253], v[64:65], v[160:161]
	v_cvt_pk_bf16_f32 v176, v252, v253
	v_pk_mul_f32 v[252:253], v[66:67], v[162:163]
	v_cvt_pk_bf16_f32 v177, v252, v253
	v_pk_mul_f32 v[252:253], v[60:61], v[156:157]
	v_cvt_pk_bf16_f32 v178, v252, v253
	v_pk_mul_f32 v[252:253], v[62:63], v[158:159]
	v_cvt_pk_bf16_f32 v179, v252, v253
	s_nop 1
	v_permlane16_swap_b32_e32 v176, v178
	v_permlane16_swap_b32_e32 v177, v179
	global_store_dwordx4 v165, v[176:179], s[10:11] offset:256
	v_add_f32_e32 v2, v2, v3
	v_mov_b32_e32 v0, v2
	s_nop 1
	v_permlane16_swap_b32_e32 v2, v0
	v_add_f32_e32 v2, v2, v0
	v_mov_b32_e32 v0, v2
	s_nop 1
	v_permlane32_swap_b32_e32 v2, v0
	v_add_f32_e32 v2, v2, v0
	v_lshrrev_b32_e32 v252, 12, v164
	v_lshlrev_b32_e32 v252, 2, v252
	s_mov_b64 exec, 0xffff
	global_atomic_add_f32 v252, v2, s[14:15]
	s_mov_b64 exec, -1
	s_branch .LBB0_188

;     __device__ __forceinline__ void operator()(const f32x4 (&acc)[2][2][4][2], const Unit& u, int wr, int wc, int fr, int fq) const {
;     ...
;         const size_t rowb = (size_t)u.pm * BM + wr * 64 + fr; const int col0 = u.pn * BM + wc * 32 + 4 * fq; const float* gb = gmod + (size_t)(u.pm >> 4) * 6144;
;         f32x4 gv[2][2], Gv[2][2];
; #pragma unroll
;         for (int bj = 0; bj < 2; ++bj)
; #pragma unroll
;             for (int n = 0; n < 2; ++n) { gv[bj][n] = *(const f32x4*)(gb + col0 + bj * HALF + n * 16);
;                 if (XG) Gv[bj][n] = *(const f32x4*)(gnorm + col0 + bj * HALF + n * 16) * (1.0f + *(const f32x4*)(scmod + (size_t)(u.pm >> 4) * 6144 + col0 + bj * HALF + n * 16)); }
.LBB0_694:
	v_mov_b32_e32 v183, v221
	s_lshl_b32 s19, s19, 8
	v_bfe_u32 v182, v183, 4, 2
	v_lshl_or_b32 v0, v182, 2, s19
	s_ashr_i32 s19, s18, 4
	v_or_b32_e32 v164, s62, v0
	s_mul_hi_i32 s38, s19, 0x6000
	s_mulk_i32 s19, 0x6000
	s_add_u32 s34, s57, s19
	v_ashrrev_i32_e32 v165, 31, v164
	s_addc_u32 s35, s58, s38
	v_lshlrev_b64 v[58:59], 2, v[164:165]
	v_lshl_add_u64 v[56:57], s[34:35], 0, v[58:59]
	global_load_dwordx4 v[72:75], v[56:57], off
	s_add_u32 s34, s30, s19
	s_addc_u32 s35, s60, s38
	v_cndmask_b32_e64 v0, 0, 1, s[12:13]
	v_lshl_add_u64 v[2:3], s[4:5], 0, v[58:59]
	v_lshl_add_u64 v[174:175], s[34:35], 0, v[58:59]
	v_cmp_ne_u32_e64 s[42:43], 1, v0
	s_andn2_b64 vcc, exec, s[12:13]
	global_load_dwordx4 v[76:79], v[56:57], off offset:64
	global_load_dwordx4 v[60:63], v[56:57], off offset:512
	s_cbranch_vccnz .Lpro_ffn2_g3
	global_load_dwordx4 v[206:209], v[174:175], off
	global_load_dwordx4 v[170:173], v[2:3], off
	global_load_dwordx4 v[210:213], v[174:175], off offset:64
	global_load_dwordx4 v[166:169], v[2:3], off offset:64
	global_load_dwordx4 v[214:217], v[174:175], off offset:512
	global_load_dwordx4 v[160:163], v[2:3], off offset:512
	global_load_dwordx4 v[176:179], v[174:175], off offset:576
	global_load_dwordx4 v[156:159], v[2:3], off offset:576

; __device__ __forceinline__ unsigned cvt_pk_bf16(float lo, float hi) { unsigned r; asm volatile("v_cvt_pk_bf16_f32 %0, %1, %2" : "=v"(r) : "v"(lo), "v"(hi)); return r; }
;     __device__ __forceinline__ void operator()(const f32x4 (&acc)[2][2][4][2], const Unit& u, int wr, int wc, int fr, int fq) const {
;     ...
;             for (int n = 0; n < 2; ++n) { gv[bj][n] = *(const f32x4*)(gb + col0 + bj * HALF + n * 16);
;                 if (XG) Gv[bj][n] = *(const f32x4*)(gnorm + col0 + bj * HALF + n * 16) * (1.0f + *(const f32x4*)(scmod + (size_t)(u.pm >> 4) * 6144 + col0 + bj * HALF + n * 16)); }
; #pragma unroll
;         for (int ai = 0; ai < 2; ++ai)
; #pragma unroll
;             for (int m = 0; m < 4; ++m) { const size_t row = rowb + ai * HALF + m * 16; const size_t off = row * 1024 + col0; float s = 0.f;
; #pragma unroll
;                 for (int bj = 0; bj < 2; ++bj) { u32x2 w[2];
; #pragma unroll
;                     for (int n = 0; n < 2; ++n) { const f32x4 xv = *(const __attribute__((address_space(1))) f32x4*)(xin + off + bj * HALF + n * 16);
;                         const f32x4 xn = xv + gv[bj][n] * acc[ai][bj][m][n];
;                         *(__attribute__((address_space(1))) f32x4*)(out + off + bj * HALF + n * 16) = xn;
;                         if (XG) { s += (xn[0] * xn[0] + xn[1] * xn[1]) + (xn[2] * xn[2] + xn[3] * xn[3]); const f32x4 t = xn * Gv[bj][n];
;                             w[n].x = cvt_pk_bf16(t[0], t[1]); w[n].y = cvt_pk_bf16(t[2], t[3]); } }
;                     if (XG) {
;                         const bool odd = (fq & 1) != 0; const u32x2 snd = odd ? w[0] : w[1]; u32x2 rcv; rcv.x = __shfl_xor(snd.x, 16); rcv.y = __shfl_xor(snd.y, 16);
;                         u32x4 o4; if (odd) { o4.x = rcv.x; o4.y = rcv.y; o4.z = w[1].x; o4.w = w[1].y; } else { o4.x = w[0].x; o4.y = w[0].y; o4.z = rcv.x; o4.w = rcv.y; }
;                         *(u32x4*)(XG + off + bj * HALF + (odd ? 12 : 0)) = o4; } }
;                 if (XG) { s += __shfl_xor(s, 16); s += __shfl_xor(s, 32); if (fq == 0) atomicAdd(ssq + row, s); } }
.LBB0_702:
	s_ashr_i32 s19, s18, 31
	s_lshl_b64 s[18:19], s[18:19], 8
	s_add_u32 s18, s18, s61
	s_addc_u32 s19, s19, s65
	v_and_or_b32 v174, v183, 15, s18
	v_mov_b32_e32 v175, s19
	s_and_b64 vcc, exec, s[42:43]
	s_cbranch_vccnz .Lepi_ffn2_orig
	v_lshlrev_b32_e32 v164, 2, v164
	v_lshl_add_u32 v164, v174, 12, v164
	v_bfe_u32 v0, v183, 4, 1
	v_lshrrev_b32_e32 v165, 1, v164
	v_mad_u32_u24 v165, v0, 24, v165
	v_mov_b32_e32 v175, v164
	v_mov_b32_e32 v2, 0
	v_mov_b32_e32 v3, 0
	global_load_dwordx4 v[182:185], v175, s[2:3] offset:0
	global_load_dwordx4 v[186:189], v175, s[2:3] offset:64
	global_load_dwordx4 v[190:193], v175, s[2:3] offset:512
	global_load_dwordx4 v[194:197], v175, s[2:3] offset:576
	v_add_u32_e32 v175, 0x10000, v175
	global_load_dwordx4 v[198:201], v175, s[2:3] offset:0
	global_load_dwordx4 v[202:205], v175, s[2:3] offset:64
	global_load_dwordx4 v[236:239], v175, s[2:3] offset:512
	global_load_dwordx4 v[240:243], v175, s[2:3] offset:576
	v_add_u32_e32 v175, 0x10000, v175
	global_load_dwordx4 v[244:247], v175, s[2:3] offset:0
	global_load_dwordx4 v[248:251], v175, s[2:3] offset:64
	s_waitcnt vmcnt(10)
	v_pk_add_f32 v[206:207], v[206:207], 1.0 op_sel_hi:[1,0]
	v_pk_add_f32 v[208:209], v[208:209], 1.0 op_sel_hi:[1,0]
	v_pk_add_f32 v[210:211], v[210:211], 1.0 op_sel_hi:[1,0]
	v_pk_add_f32 v[212:213], v[212:213], 1.0 op_sel_hi:[1,0]
	v_pk_add_f32 v[214:215], v[214:215], 1.0 op_sel_hi:[1,0]
	v_pk_add_f32 v[216:217], v[216:217], 1.0 op_sel_hi:[1,0]
	v_pk_add_f32 v[176:177], v[176:177], 1.0 op_sel_hi:[1,0]
	v_pk_add_f32 v[178:179], v[178:179], 1.0 op_sel_hi:[1,0]
	v_pk_mul_f32 v[170:171], v[170:171], v[206:207]
	v_pk_mul_f32 v[172:173], v[172:173], v[208:209]
	v_pk_mul_f32 v[166:167], v[166:167], v[210:211]
	v_pk_mul_f32 v[168:169], v[168:169], v[212:213]
	v_pk_mul_f32 v[160:161], v[160:161], v[214:215]
	v_pk_mul_f32 v[162:163], v[162:163], v[216:217]
	v_pk_mul_f32 v[156:157], v[156:157], v[176:177]
	v_pk_mul_f32 v[158:159], v[158:159], v[178:179]
	s_waitcnt vmcnt(8)
	v_pk_fma_f32 v[182:183], v[64:65], v[72:73], v[182:183]
	v_pk_fma_f32 v[184:185], v[66:67], v[74:75], v[184:185]
	v_pk_fma_f32 v[186:187], v[144:145], v[76:77], v[186:187]
	v_pk_fma_f32 v[188:189], v[146:147], v[78:79], v[188:189]
	global_store_dwordx4 v164, v[182:185], s[2:3] offset:0
	global_store_dwordx4 v164, v[186:189], s[2:3] offset:64
	global_load_dwordx4 v[64:67], v175, s[2:3] offset:512
	global_load_dwordx4 v[144:147], v175, s[2:3] offset:576
	v_add_u32_e32 v175, 0x10000, v175
	v_pk_fma_f32 v[2:3], v[182:183], v[182:183], v[2:3]
	v_pk_fma_f32 v[2:3], v[184:185], v[184:185], v[2:3]
	v_pk_fma_f32 v[2:3], v[186:187], v[186:187], v[2:3]
	v_pk_fma_f32 v[2:3], v[188:189], v[188:189], v[2:3]
	v_pk_mul_f32 v[252:253], v[182:183], v[170:171]
	v_cvt_pk_bf16_f32 v176, v252, v253
	v_pk_mul_f32 v[252:253], v[184:185], v[172:173]
	v_cvt_pk_bf16_f32 v177, v252, v253
	v_pk_mul_f32 v[252:253], v[186:187], v[166:167]
	v_cvt_pk_bf16_f32 v178, v252, v253
	v_pk_mul_f32 v[252:253], v[188:189], v[168:169]
	v_cvt_pk_bf16_f32 v179, v252, v253
	s_nop 1
	v_permlane16_swap_b32_e32 v176, v178
	v_permlane16_swap_b32_e32 v177, v179
	global_store_dwordx4 v165, v[176:179], s[92:93] offset:0
	s_waitcnt vmcnt(11)
	v_pk_fma_f32 v[190:191], v[140:141], v[60:61], v[190:191]
	v_pk_fma_f32 v[192:193], v[142:143], v[62:63], v[192:193]
	v_pk_fma_f32 v[194:195], v[136:137], v[56:57], v[194:195]
	v_pk_fma_f32 v[196:197], v[138:139], v[58:59], v[196:197]
	global_store_dwordx4 v164, v[190:193], s[2:3] offset:512
	global_store_dwordx4 v164, v[194:197], s[2:3] offset:576
	global_load_dwordx4 v[140:143], v175, s[2:3] offset:0
	global_load_dwordx4 v[136:139], v175, s[2:3] offset:64
	v_pk_fma_f32 v[2:3], v[190:191], v[190:191], v[2:3]
	v_pk_fma_f32 v[2:3], v[192:193], v[192:193], v[2:3]
	v_pk_fma_f32 v[2:3], v[194:195], v[194:195], v[2:3]
	v_pk_fma_f32 v[2:3], v[196:197], v[196:197], v[2:3]
	v_pk_mul_f32 v[252:253], v[190:191], v[160:161]
	v_cvt_pk_bf16_f32 v176, v252, v253
	v_pk_mul_f32 v[252:253], v[192:193], v[162:163]
	v_cvt_pk_bf16_f32 v177, v252, v253
	v_pk_mul_f32 v[252:253], v[194:195], v[156:157]
	v_cvt_pk_bf16_f32 v178, v252, v253
	v_pk_mul_f32 v[252:253], v[196:197], v[158:159]
	v_cvt_pk_bf16_f32 v179, v252, v253
	s_nop 1
	v_permlane16_swap_b32_e32 v176, v178
	v_permlane16_swap_b32_e32 v177, v179
	global_store_dwordx4 v165, v[176:179], s[92:93] offset:256
	v_add_f32_e32 v2, v2, v3
	v_mov_b32_e32 v0, v2
	s_nop 1
	v_permlane16_swap_b32_e32 v2, v0
	v_add_f32_e32 v2, v2, v0
	v_mov_b32_e32 v0, v2
	s_nop 1
	v_permlane32_swap_b32_e32 v2, v0
	v_add_f32_e32 v2, v2, v0
	v_lshrrev_b32_e32 v252, 12, v164
	v_lshlrev_b32_e32 v252, 2, v252
	s_mov_b64 exec, 0xffff
	global_atomic_add_f32 v252, v2, s[8:9]
	s_mov_b64 exec, -1
	v_add_u32_e32 v164, 0x10000, v164
	v_add_u32_e32 v165, 0x8000, v165
	v_mov_b32_e32 v2, 0
	v_mov_b32_e32 v3, 0
	s_waitcnt vmcnt(15)
	v_pk_fma_f32 v[198:199], v[132:133], v[72:73], v[198:199]
	v_pk_fma_f32 v[200:201], v[134:135], v[74:75], v[200:201]
	v_pk_fma_f32 v[202:203], v[128:129], v[76:77], v[202:203]
	v_pk_fma_f32 v[204:205], v[130:131], v[78:79], v[204:205]
	global_store_dwordx4 v164, v[198:201], s[2:3] offset:0
	global_store_dwordx4 v164, v[202:205], s[2:3] offset:64
	global_load_dwordx4 v[132:135], v175, s[2:3] offset:512
	global_load_dwordx4 v[128:131], v175, s[2:3] offset:576
	v_add_u32_e32 v175, 0x50000, v175
	v_pk_fma_f32 v[2:3], v[198:199], v[198:199], v[2:3]
	v_pk_fma_f32 v[2:3], v[200:201], v[200:201], v[2:3]
	v_pk_fma_f32 v[2:3], v[202:203], v[202:203], v[2:3]
	v_pk_fma_f32 v[2:3], v[204:205], v[204:205], v[2:3]
	v_pk_mul_f32 v[252:253], v[198:199], v[170:171]
	v_cvt_pk_bf16_f32 v176, v252, v253
	v_pk_mul_f32 v[252:253], v[200:201], v[172:173]
	v_cvt_pk_bf16_f32 v177, v252, v253
	v_pk_mul_f32 v[252:253], v[202:203], v[166:167]
	v_cvt_pk_bf16_f32 v178, v252, v253
	v_pk_mul_f32 v[252:253], v[204:205], v[168:169]
	v_cvt_pk_bf16_f32 v179, v252, v253
	s_nop 1
	v_permlane16_swap_b32_e32 v176, v178
	v_permlane16_swap_b32_e32 v177, v179
	global_store_dwordx4 v165, v[176:179], s[92:93] offset:0
	s_waitcnt vmcnt(18)
; __device__ __forceinline__ unsigned cvt_pk_bf16(float lo, float hi) { unsigned r; asm volatile("v_cvt_pk_bf16_f32 %0, %1, %2" : "=v"(r) : "v"(lo), "v"(hi)); return r; }
;     __device__ __forceinline__ void operator()(const f32x4 (&acc)[2][2][4][2], const Unit& u, int wr, int wc, int fr, int fq) const {
;     ...
;             for (int m = 0; m < 4; ++m) { const size_t row = rowb + ai * HALF + m * 16; const size_t off = row * 1024 + col0; float s = 0.f;
; #pragma unroll
;                 for (int bj = 0; bj < 2; ++bj) { u32x2 w[2];
; #pragma unroll
;                     for (int n = 0; n < 2; ++n) { const f32x4 xv = *(const __attribute__((address_space(1))) f32x4*)(xin + off + bj * HALF + n * 16);
;                         const f32x4 xn = xv + gv[bj][n] * acc[ai][bj][m][n];
;                         *(__attribute__((address_space(1))) f32x4*)(out + off + bj * HALF + n * 16) = xn;
;                         if (XG) { s += (xn[0] * xn[0] + xn[1] * xn[1]) + (xn[2] * xn[2] + xn[3] * xn[3]); const f32x4 t = xn * Gv[bj][n];
;                             w[n].x = cvt_pk_bf16(t[0], t[1]); w[n].y = cvt_pk_bf16(t[2], t[3]); } }
;                     if (XG) {
;                         const bool odd = (fq & 1) != 0; const u32x2 snd = odd ? w[0] : w[1]; u32x2 rcv; rcv.x = __shfl_xor(snd.x, 16); rcv.y = __shfl_xor(snd.y, 16);
;                         u32x4 o4; if (odd) { o4.x = rcv.x; o4.y = rcv.y; o4.z = w[1].x; o4.w = w[1].y; } else { o4.x = w[0].x; o4.y = w[0].y; o4.z = rcv.x; o4.w = rcv.y; }
;                         *(u32x4*)(XG + off + bj * HALF + (odd ? 12 : 0)) = o4; } }
;                 if (XG) { s += __shfl_xor(s, 16); s += __shfl_xor(s, 32); if (fq == 0) atomicAdd(ssq + row, s); } }
	v_pk_fma_f32 v[236:237], v[124:125], v[60:61], v[236:237]
	v_pk_fma_f32 v[238:239], v[126:127], v[62:63], v[238:239]
	v_pk_fma_f32 v[240:241], v[120:121], v[56:57], v[240:241]
	v_pk_fma_f32 v[242:243], v[122:123], v[58:59], v[242:243]
	global_store_dwordx4 v164, v[236:239], s[2:3] offset:512
	global_store_dwordx4 v164, v[240:243], s[2:3] offset:576
	global_load_dwordx4 v[124:127], v175, s[2:3] offset:0
	global_load_dwordx4 v[120:123], v175, s[2:3] offset:64
	v_pk_fma_f32 v[2:3], v[236:237], v[236:237], v[2:3]
	v_pk_fma_f32 v[2:3], v[238:239], v[238:239], v[2:3]
	v_pk_fma_f32 v[2:3], v[240:241], v[240:241], v[2:3]
	v_pk_fma_f32 v[2:3], v[242:243], v[242:243], v[2:3]
	v_pk_mul_f32 v[252:253], v[236:237], v[160:161]
	v_cvt_pk_bf16_f32 v176, v252, v253
	v_pk_mul_f32 v[252:253], v[238:239], v[162:163]
	v_cvt_pk_bf16_f32 v177, v252, v253
	v_pk_mul_f32 v[252:253], v[240:241], v[156:157]
	v_cvt_pk_bf16_f32 v178, v252, v253
	v_pk_mul_f32 v[252:253], v[242:243], v[158:159]
	v_cvt_pk_bf16_f32 v179, v252, v253
	s_nop 1
	v_permlane16_swap_b32_e32 v176, v178
	v_permlane16_swap_b32_e32 v177, v179
	global_store_dwordx4 v165, v[176:179], s[92:93] offset:256
	v_add_f32_e32 v2, v2, v3
	v_mov_b32_e32 v0, v2
	s_nop 1
	v_permlane16_swap_b32_e32 v2, v0
	v_add_f32_e32 v2, v2, v0
	v_mov_b32_e32 v0, v2
	s_nop 1
	v_permlane32_swap_b32_e32 v2, v0
	v_add_f32_e32 v2, v2, v0
	v_lshrrev_b32_e32 v252, 12, v164
	v_lshlrev_b32_e32 v252, 2, v252
	s_mov_b64 exec, 0xffff
	global_atomic_add_f32 v252, v2, s[8:9]
	s_mov_b64 exec, -1
	v_add_u32_e32 v164, 0x10000, v164
	v_add_u32_e32 v165, 0x8000, v165
	v_mov_b32_e32 v2, 0
	v_mov_b32_e32 v3, 0
	s_waitcnt vmcnt(22)
	v_pk_fma_f32 v[244:245], v[116:117], v[72:73], v[244:245]
	v_pk_fma_f32 v[246:247], v[118:119], v[74:75], v[246:247]
	v_pk_fma_f32 v[248:249], v[112:113], v[76:77], v[248:249]
	v_pk_fma_f32 v[250:251], v[114:115], v[78:79], v[250:251]
	global_store_dwordx4 v164, v[244:247], s[2:3] offset:0
	global_store_dwordx4 v164, v[248:251], s[2:3] offset:64
	global_load_dwordx4 v[116:119], v175, s[2:3] offset:512
	global_load_dwordx4 v[112:115], v175, s[2:3] offset:576
	v_add_u32_e32 v175, 0x10000, v175
	v_pk_fma_f32 v[2:3], v[244:245], v[244:245], v[2:3]
	v_pk_fma_f32 v[2:3], v[246:247], v[246:247], v[2:3]
	v_pk_fma_f32 v[2:3], v[248:249], v[248:249], v[2:3]
	v_pk_fma_f32 v[2:3], v[250:251], v[250:251], v[2:3]
	v_pk_mul_f32 v[252:253], v[244:245], v[170:171]
	v_cvt_pk_bf16_f32 v176, v252, v253
	v_pk_mul_f32 v[252:253], v[246:247], v[172:173]
	v_cvt_pk_bf16_f32 v177, v252, v253
	v_pk_mul_f32 v[252:253], v[248:249], v[166:167]
	v_cvt_pk_bf16_f32 v178, v252, v253
	v_pk_mul_f32 v[252:253], v[250:251], v[168:169]
	v_cvt_pk_bf16_f32 v179, v252, v253
	s_nop 1
	v_permlane16_swap_b32_e32 v176, v178
	v_permlane16_swap_b32_e32 v177, v179
	global_store_dwordx4 v165, v[176:179], s[92:93] offset:0
	s_waitcnt vmcnt(23)
	v_pk_fma_f32 v[64:65], v[108:109], v[60:61], v[64:65]
	v_pk_fma_f32 v[66:67], v[110:111], v[62:63], v[66:67]
	v_pk_fma_f32 v[144:145], v[104:105], v[56:57], v[144:145]
	v_pk_fma_f32 v[146:147], v[106:107], v[58:59], v[146:147]
	global_store_dwordx4 v164, v[64:67], s[2:3] offset:512
	global_store_dwordx4 v164, v[144:147], s[2:3] offset:576
	global_load_dwordx4 v[108:111], v175, s[2:3] offset:0
	global_load_dwordx4 v[104:107], v175, s[2:3] offset:64
	v_pk_fma_f32 v[2:3], v[64:65], v[64:65], v[2:3]
	v_pk_fma_f32 v[2:3], v[66:67], v[66:67], v[2:3]
	v_pk_fma_f32 v[2:3], v[144:145], v[144:145], v[2:3]
	v_pk_fma_f32 v[2:3], v[146:147], v[146:147], v[2:3]
	v_pk_mul_f32 v[252:253], v[64:65], v[160:161]
	v_cvt_pk_bf16_f32 v176, v252, v253
	v_pk_mul_f32 v[252:253], v[66:67], v[162:163]
	v_cvt_pk_bf16_f32 v177, v252, v253
	v_pk_mul_f32 v[252:253], v[144:145], v[156:157]
	v_cvt_pk_bf16_f32 v178, v252, v253
	v_pk_mul_f32 v[252:253], v[146:147], v[158:159]
	v_cvt_pk_bf16_f32 v179, v252, v253
	s_nop 1
	v_permlane16_swap_b32_e32 v176, v178
	v_permlane16_swap_b32_e32 v177, v179
	global_store_dwordx4 v165, v[176:179], s[92:93] offset:256
	v_add_f32_e32 v2, v2, v3
	v_mov_b32_e32 v0, v2
	s_nop 1
	v_permlane16_swap_b32_e32 v2, v0
	v_add_f32_e32 v2, v2, v0
	v_mov_b32_e32 v0, v2
	s_nop 1
	v_permlane32_swap_b32_e32 v2, v0
	v_add_f32_e32 v2, v2, v0
	v_lshrrev_b32_e32 v252, 12, v164
	v_lshlrev_b32_e32 v252, 2, v252
	s_mov_b64 exec, 0xffff
	global_atomic_add_f32 v252, v2, s[8:9]
	s_mov_b64 exec, -1
	v_add_u32_e32 v164, 0x10000, v164
	v_add_u32_e32 v165, 0x8000, v165
	v_mov_b32_e32 v2, 0
	v_mov_b32_e32 v3, 0
	s_waitcnt vmcnt(24)
	v_pk_fma_f32 v[140:141], v[100:101], v[72:73], v[140:141]
	v_pk_fma_f32 v[142:143], v[102:103], v[74:75], v[142:143]
	v_pk_fma_f32 v[136:137], v[96:97], v[76:77], v[136:137]
	v_pk_fma_f32 v[138:139], v[98:99], v[78:79], v[138:139]
	global_store_dwordx4 v164, v[140:143], s[2:3] offset:0
	global_store_dwordx4 v164, v[136:139], s[2:3] offset:64
	global_load_dwordx4 v[100:103], v175, s[2:3] offset:512
	global_load_dwordx4 v[96:99], v175, s[2:3] offset:576
	v_add_u32_e32 v175, 0x10000, v175
	v_pk_fma_f32 v[2:3], v[140:141], v[140:141], v[2:3]
	v_pk_fma_f32 v[2:3], v[142:143], v[142:143], v[2:3]
	v_pk_fma_f32 v[2:3], v[136:137], v[136:137], v[2:3]
	v_pk_fma_f32 v[2:3], v[138:139], v[138:139], v[2:3]
	v_pk_mul_f32 v[252:253], v[140:141], v[170:171]
	v_cvt_pk_bf16_f32 v176, v252, v253
	v_pk_mul_f32 v[252:253], v[142:143], v[172:173]
	v_cvt_pk_bf16_f32 v177, v252, v253
	v_pk_mul_f32 v[252:253], v[136:137], v[166:167]
	v_cvt_pk_bf16_f32 v178, v252, v253
	v_pk_mul_f32 v[252:253], v[138:139], v[168:169]
	v_cvt_pk_bf16_f32 v179, v252, v253
	s_nop 1
	v_permlane16_swap_b32_e32 v176, v178
	v_permlane16_swap_b32_e32 v177, v179
	global_store_dwordx4 v165, v[176:179], s[92:93] offset:0
	s_waitcnt vmcnt(23)
; __device__ __forceinline__ unsigned cvt_pk_bf16(float lo, float hi) { unsigned r; asm volatile("v_cvt_pk_bf16_f32 %0, %1, %2" : "=v"(r) : "v"(lo), "v"(hi)); return r; }
;     __device__ __forceinline__ void operator()(const f32x4 (&acc)[2][2][4][2], const Unit& u, int wr, int wc, int fr, int fq) const {
;     ...
;             for (int m = 0; m < 4; ++m) { const size_t row = rowb + ai * HALF + m * 16; const size_t off = row * 1024 + col0; float s = 0.f;
; #pragma unroll
;                 for (int bj = 0; bj < 2; ++bj) { u32x2 w[2];
; #pragma unroll
;                     for (int n = 0; n < 2; ++n) { const f32x4 xv = *(const __attribute__((address_space(1))) f32x4*)(xin + off + bj * HALF + n * 16);
;                         const f32x4 xn = xv + gv[bj][n] * acc[ai][bj][m][n];
;                         *(__attribute__((address_space(1))) f32x4*)(out + off + bj * HALF + n * 16) = xn;
;                         if (XG) { s += (xn[0] * xn[0] + xn[1] * xn[1]) + (xn[2] * xn[2] + xn[3] * xn[3]); const f32x4 t = xn * Gv[bj][n];
;                             w[n].x = cvt_pk_bf16(t[0], t[1]); w[n].y = cvt_pk_bf16(t[2], t[3]); } }
;                     if (XG) {
;                         const bool odd = (fq & 1) != 0; const u32x2 snd = odd ? w[0] : w[1]; u32x2 rcv; rcv.x = __shfl_xor(snd.x, 16); rcv.y = __shfl_xor(snd.y, 16);
;                         u32x4 o4; if (odd) { o4.x = rcv.x; o4.y = rcv.y; o4.z = w[1].x; o4.w = w[1].y; } else { o4.x = w[0].x; o4.y = w[0].y; o4.z = rcv.x; o4.w = rcv.y; }
;                         *(u32x4*)(XG + off + bj * HALF + (odd ? 12 : 0)) = o4; } }
;                 if (XG) { s += __shfl_xor(s, 16); s += __shfl_xor(s, 32); if (fq == 0) atomicAdd(ssq + row, s); } }
	v_pk_fma_f32 v[132:133], v[92:93], v[60:61], v[132:133]
	v_pk_fma_f32 v[134:135], v[94:95], v[62:63], v[134:135]
	v_pk_fma_f32 v[128:129], v[88:89], v[56:57], v[128:129]
	v_pk_fma_f32 v[130:131], v[90:91], v[58:59], v[130:131]
	global_store_dwordx4 v164, v[132:135], s[2:3] offset:512
	global_store_dwordx4 v164, v[128:131], s[2:3] offset:576
	global_load_dwordx4 v[92:95], v175, s[2:3] offset:0
	global_load_dwordx4 v[88:91], v175, s[2:3] offset:64
	v_pk_fma_f32 v[2:3], v[132:133], v[132:133], v[2:3]
	v_pk_fma_f32 v[2:3], v[134:135], v[134:135], v[2:3]
	v_pk_fma_f32 v[2:3], v[128:129], v[128:129], v[2:3]
	v_pk_fma_f32 v[2:3], v[130:131], v[130:131], v[2:3]
	v_pk_mul_f32 v[252:253], v[132:133], v[160:161]
	v_cvt_pk_bf16_f32 v176, v252, v253
	v_pk_mul_f32 v[252:253], v[134:135], v[162:163]
	v_cvt_pk_bf16_f32 v177, v252, v253
	v_pk_mul_f32 v[252:253], v[128:129], v[156:157]
	v_cvt_pk_bf16_f32 v178, v252, v253
	v_pk_mul_f32 v[252:253], v[130:131], v[158:159]
	v_cvt_pk_bf16_f32 v179, v252, v253
	s_nop 1
	v_permlane16_swap_b32_e32 v176, v178
	v_permlane16_swap_b32_e32 v177, v179
	global_store_dwordx4 v165, v[176:179], s[92:93] offset:256
	v_add_f32_e32 v2, v2, v3
	v_mov_b32_e32 v0, v2
	s_nop 1
	v_permlane16_swap_b32_e32 v2, v0
	v_add_f32_e32 v2, v2, v0
	v_mov_b32_e32 v0, v2
	s_nop 1
	v_permlane32_swap_b32_e32 v2, v0
	v_add_f32_e32 v2, v2, v0
	v_lshrrev_b32_e32 v252, 12, v164
	v_lshlrev_b32_e32 v252, 2, v252
	s_mov_b64 exec, 0xffff
	global_atomic_add_f32 v252, v2, s[8:9]
	s_mov_b64 exec, -1
	v_add_u32_e32 v164, 0x50000, v164
	v_add_u32_e32 v165, 0x28000, v165
	v_mov_b32_e32 v2, 0
	v_mov_b32_e32 v3, 0
	s_waitcnt vmcnt(24)
	v_pk_fma_f32 v[124:125], v[84:85], v[72:73], v[124:125]
	v_pk_fma_f32 v[126:127], v[86:87], v[74:75], v[126:127]
	v_pk_fma_f32 v[120:121], v[80:81], v[76:77], v[120:121]
	v_pk_fma_f32 v[122:123], v[82:83], v[78:79], v[122:123]
	global_store_dwordx4 v164, v[124:127], s[2:3] offset:0
	global_store_dwordx4 v164, v[120:123], s[2:3] offset:64
	global_load_dwordx4 v[84:87], v175, s[2:3] offset:512
	global_load_dwordx4 v[80:83], v175, s[2:3] offset:576
	v_add_u32_e32 v175, 0x10000, v175
	v_pk_fma_f32 v[2:3], v[124:125], v[124:125], v[2:3]
	v_pk_fma_f32 v[2:3], v[126:127], v[126:127], v[2:3]
	v_pk_fma_f32 v[2:3], v[120:121], v[120:121], v[2:3]
	v_pk_fma_f32 v[2:3], v[122:123], v[122:123], v[2:3]
	v_pk_mul_f32 v[252:253], v[124:125], v[170:171]
	v_cvt_pk_bf16_f32 v176, v252, v253
	v_pk_mul_f32 v[252:253], v[126:127], v[172:173]
	v_cvt_pk_bf16_f32 v177, v252, v253
	v_pk_mul_f32 v[252:253], v[120:121], v[166:167]
	v_cvt_pk_bf16_f32 v178, v252, v253
	v_pk_mul_f32 v[252:253], v[122:123], v[168:169]
	v_cvt_pk_bf16_f32 v179, v252, v253
	s_nop 1
	v_permlane16_swap_b32_e32 v176, v178
	v_permlane16_swap_b32_e32 v177, v179
	global_store_dwordx4 v165, v[176:179], s[92:93] offset:0
	s_waitcnt vmcnt(23)
	v_pk_fma_f32 v[116:117], v[68:69], v[60:61], v[116:117]
	v_pk_fma_f32 v[118:119], v[70:71], v[62:63], v[118:119]
	v_pk_fma_f32 v[112:113], v[52:53], v[56:57], v[112:113]
	v_pk_fma_f32 v[114:115], v[54:55], v[58:59], v[114:115]
	global_store_dwordx4 v164, v[116:119], s[2:3] offset:512
	global_store_dwordx4 v164, v[112:115], s[2:3] offset:576
	global_load_dwordx4 v[68:71], v175, s[2:3] offset:0
	global_load_dwordx4 v[52:55], v175, s[2:3] offset:64
	v_pk_fma_f32 v[2:3], v[116:117], v[116:117], v[2:3]
	v_pk_fma_f32 v[2:3], v[118:119], v[118:119], v[2:3]
	v_pk_fma_f32 v[2:3], v[112:113], v[112:113], v[2:3]
	v_pk_fma_f32 v[2:3], v[114:115], v[114:115], v[2:3]
	v_pk_mul_f32 v[252:253], v[116:117], v[160:161]
	v_cvt_pk_bf16_f32 v176, v252, v253
	v_pk_mul_f32 v[252:253], v[118:119], v[162:163]
	v_cvt_pk_bf16_f32 v177, v252, v253
	v_pk_mul_f32 v[252:253], v[112:113], v[156:157]
	v_cvt_pk_bf16_f32 v178, v252, v253
	v_pk_mul_f32 v[252:253], v[114:115], v[158:159]
	v_cvt_pk_bf16_f32 v179, v252, v253
	s_nop 1
	v_permlane16_swap_b32_e32 v176, v178
	v_permlane16_swap_b32_e32 v177, v179
	global_store_dwordx4 v165, v[176:179], s[92:93] offset:256
	v_add_f32_e32 v2, v2, v3
	v_mov_b32_e32 v0, v2
	s_nop 1
	v_permlane16_swap_b32_e32 v2, v0
	v_add_f32_e32 v2, v2, v0
	v_mov_b32_e32 v0, v2
	s_nop 1
	v_permlane32_swap_b32_e32 v2, v0
	v_add_f32_e32 v2, v2, v0
	v_lshrrev_b32_e32 v252, 12, v164
	v_lshlrev_b32_e32 v252, 2, v252
	s_mov_b64 exec, 0xffff
	global_atomic_add_f32 v252, v2, s[8:9]
	s_mov_b64 exec, -1
	v_add_u32_e32 v164, 0x10000, v164
	v_add_u32_e32 v165, 0x8000, v165
	v_mov_b32_e32 v2, 0
	v_mov_b32_e32 v3, 0
	s_waitcnt vmcnt(24)
	v_pk_fma_f32 v[108:109], v[48:49], v[72:73], v[108:109]
	v_pk_fma_f32 v[110:111], v[50:51], v[74:75], v[110:111]
	v_pk_fma_f32 v[104:105], v[44:45], v[76:77], v[104:105]
	v_pk_fma_f32 v[106:107], v[46:47], v[78:79], v[106:107]
	global_store_dwordx4 v164, v[108:111], s[2:3] offset:0
	global_store_dwordx4 v164, v[104:107], s[2:3] offset:64
	global_load_dwordx4 v[48:51], v175, s[2:3] offset:512
	global_load_dwordx4 v[44:47], v175, s[2:3] offset:576
	v_pk_fma_f32 v[2:3], v[108:109], v[108:109], v[2:3]
	v_pk_fma_f32 v[2:3], v[110:111], v[110:111], v[2:3]
	v_pk_fma_f32 v[2:3], v[104:105], v[104:105], v[2:3]
	v_pk_fma_f32 v[2:3], v[106:107], v[106:107], v[2:3]
	v_pk_mul_f32 v[252:253], v[108:109], v[170:171]
	v_cvt_pk_bf16_f32 v176, v252, v253
	v_pk_mul_f32 v[252:253], v[110:111], v[172:173]
	v_cvt_pk_bf16_f32 v177, v252, v253
	v_pk_mul_f32 v[252:253], v[104:105], v[166:167]
	v_cvt_pk_bf16_f32 v178, v252, v253
	v_pk_mul_f32 v[252:253], v[106:107], v[168:169]
	v_cvt_pk_bf16_f32 v179, v252, v253
	s_nop 1
	v_permlane16_swap_b32_e32 v176, v178
	v_permlane16_swap_b32_e32 v177, v179
	global_store_dwordx4 v165, v[176:179], s[92:93] offset:0
	s_waitcnt vmcnt(23)
; __device__ __forceinline__ unsigned cvt_pk_bf16(float lo, float hi) { unsigned r; asm volatile("v_cvt_pk_bf16_f32 %0, %1, %2" : "=v"(r) : "v"(lo), "v"(hi)); return r; }
;     __device__ __forceinline__ void operator()(const f32x4 (&acc)[2][2][4][2], const Unit& u, int wr, int wc, int fr, int fq) const {
;     ...
;             for (int m = 0; m < 4; ++m) { const size_t row = rowb + ai * HALF + m * 16; const size_t off = row * 1024 + col0; float s = 0.f;
; #pragma unroll
;                 for (int bj = 0; bj < 2; ++bj) { u32x2 w[2];
; #pragma unroll
;                     for (int n = 0; n < 2; ++n) { const f32x4 xv = *(const __attribute__((address_space(1))) f32x4*)(xin + off + bj * HALF + n * 16);
;                         const f32x4 xn = xv + gv[bj][n] * acc[ai][bj][m][n];
;                         *(__attribute__((address_space(1))) f32x4*)(out + off + bj * HALF + n * 16) = xn;
;                         if (XG) { s += (xn[0] * xn[0] + xn[1] * xn[1]) + (xn[2] * xn[2] + xn[3] * xn[3]); const f32x4 t = xn * Gv[bj][n];
;                             w[n].x = cvt_pk_bf16(t[0], t[1]); w[n].y = cvt_pk_bf16(t[2], t[3]); } }
;                     if (XG) {
;                         const bool odd = (fq & 1) != 0; const u32x2 snd = odd ? w[0] : w[1]; u32x2 rcv; rcv.x = __shfl_xor(snd.x, 16); rcv.y = __shfl_xor(snd.y, 16);
;                         u32x4 o4; if (odd) { o4.x = rcv.x; o4.y = rcv.y; o4.z = w[1].x; o4.w = w[1].y; } else { o4.x = w[0].x; o4.y = w[0].y; o4.z = rcv.x; o4.w = rcv.y; }
;                         *(u32x4*)(XG + off + bj * HALF + (odd ? 12 : 0)) = o4; } }
;                 if (XG) { s += __shfl_xor(s, 16); s += __shfl_xor(s, 32); if (fq == 0) atomicAdd(ssq + row, s); } }
	v_pk_fma_f32 v[100:101], v[40:41], v[60:61], v[100:101]
	v_pk_fma_f32 v[102:103], v[42:43], v[62:63], v[102:103]
	v_pk_fma_f32 v[96:97], v[36:37], v[56:57], v[96:97]
	v_pk_fma_f32 v[98:99], v[38:39], v[58:59], v[98:99]
	global_store_dwordx4 v164, v[100:103], s[2:3] offset:512
	global_store_dwordx4 v164, v[96:99], s[2:3] offset:576
	v_pk_fma_f32 v[2:3], v[100:101], v[100:101], v[2:3]
	v_pk_fma_f32 v[2:3], v[102:103], v[102:103], v[2:3]
	v_pk_fma_f32 v[2:3], v[96:97], v[96:97], v[2:3]
	v_pk_fma_f32 v[2:3], v[98:99], v[98:99], v[2:3]
	v_pk_mul_f32 v[252:253], v[100:101], v[160:161]
	v_cvt_pk_bf16_f32 v176, v252, v253
	v_pk_mul_f32 v[252:253], v[102:103], v[162:163]
	v_cvt_pk_bf16_f32 v177, v252, v253
	v_pk_mul_f32 v[252:253], v[96:97], v[156:157]
	v_cvt_pk_bf16_f32 v178, v252, v253
	v_pk_mul_f32 v[252:253], v[98:99], v[158:159]
	v_cvt_pk_bf16_f32 v179, v252, v253
	s_nop 1
	v_permlane16_swap_b32_e32 v176, v178
	v_permlane16_swap_b32_e32 v177, v179
	global_store_dwordx4 v165, v[176:179], s[92:93] offset:256
	v_add_f32_e32 v2, v2, v3
	v_mov_b32_e32 v0, v2
	s_nop 1
	v_permlane16_swap_b32_e32 v2, v0
	v_add_f32_e32 v2, v2, v0
	v_mov_b32_e32 v0, v2
	s_nop 1
	v_permlane32_swap_b32_e32 v2, v0
	v_add_f32_e32 v2, v2, v0
	v_lshrrev_b32_e32 v252, 12, v164
	v_lshlrev_b32_e32 v252, 2, v252
	s_mov_b64 exec, 0xffff
	global_atomic_add_f32 v252, v2, s[8:9]
	s_mov_b64 exec, -1
	v_add_u32_e32 v164, 0x10000, v164
	v_add_u32_e32 v165, 0x8000, v165
	v_mov_b32_e32 v2, 0
	v_mov_b32_e32 v3, 0
	s_waitcnt vmcnt(22)
	v_pk_fma_f32 v[92:93], v[32:33], v[72:73], v[92:93]
	v_pk_fma_f32 v[94:95], v[34:35], v[74:75], v[94:95]
	v_pk_fma_f32 v[88:89], v[28:29], v[76:77], v[88:89]
	v_pk_fma_f32 v[90:91], v[30:31], v[78:79], v[90:91]
	global_store_dwordx4 v164, v[92:95], s[2:3] offset:0
	global_store_dwordx4 v164, v[88:91], s[2:3] offset:64
	v_pk_fma_f32 v[2:3], v[92:93], v[92:93], v[2:3]
	v_pk_fma_f32 v[2:3], v[94:95], v[94:95], v[2:3]
	v_pk_fma_f32 v[2:3], v[88:89], v[88:89], v[2:3]
	v_pk_fma_f32 v[2:3], v[90:91], v[90:91], v[2:3]
	v_pk_mul_f32 v[252:253], v[92:93], v[170:171]
	v_cvt_pk_bf16_f32 v176, v252, v253
	v_pk_mul_f32 v[252:253], v[94:95], v[172:173]
	v_cvt_pk_bf16_f32 v177, v252, v253
	v_pk_mul_f32 v[252:253], v[88:89], v[166:167]
	v_cvt_pk_bf16_f32 v178, v252, v253
	v_pk_mul_f32 v[252:253], v[90:91], v[168:169]
	v_cvt_pk_bf16_f32 v179, v252, v253
	s_nop 1
	v_permlane16_swap_b32_e32 v176, v178
	v_permlane16_swap_b32_e32 v177, v179
	global_store_dwordx4 v165, v[176:179], s[92:93] offset:0
	s_waitcnt vmcnt(19)
	v_pk_fma_f32 v[84:85], v[24:25], v[60:61], v[84:85]
	v_pk_fma_f32 v[86:87], v[26:27], v[62:63], v[86:87]
	v_pk_fma_f32 v[80:81], v[20:21], v[56:57], v[80:81]
	v_pk_fma_f32 v[82:83], v[22:23], v[58:59], v[82:83]
	global_store_dwordx4 v164, v[84:87], s[2:3] offset:512
	global_store_dwordx4 v164, v[80:83], s[2:3] offset:576
	v_pk_fma_f32 v[2:3], v[84:85], v[84:85], v[2:3]
	v_pk_fma_f32 v[2:3], v[86:87], v[86:87], v[2:3]
	v_pk_fma_f32 v[2:3], v[80:81], v[80:81], v[2:3]
	v_pk_fma_f32 v[2:3], v[82:83], v[82:83], v[2:3]
	v_pk_mul_f32 v[252:253], v[84:85], v[160:161]
	v_cvt_pk_bf16_f32 v176, v252, v253
	v_pk_mul_f32 v[252:253], v[86:87], v[162:163]
	v_cvt_pk_bf16_f32 v177, v252, v253
	v_pk_mul_f32 v[252:253], v[80:81], v[156:157]
	v_cvt_pk_bf16_f32 v178, v252, v253
	v_pk_mul_f32 v[252:253], v[82:83], v[158:159]
	v_cvt_pk_bf16_f32 v179, v252, v253
	s_nop 1
	v_permlane16_swap_b32_e32 v176, v178
	v_permlane16_swap_b32_e32 v177, v179
	global_store_dwordx4 v165, v[176:179], s[92:93] offset:256
	v_add_f32_e32 v2, v2, v3
	v_mov_b32_e32 v0, v2
	s_nop 1
	v_permlane16_swap_b32_e32 v2, v0
	v_add_f32_e32 v2, v2, v0
	v_mov_b32_e32 v0, v2
	s_nop 1
	v_permlane32_swap_b32_e32 v2, v0
	v_add_f32_e32 v2, v2, v0
	v_lshrrev_b32_e32 v252, 12, v164
	v_lshlrev_b32_e32 v252, 2, v252
	s_mov_b64 exec, 0xffff
	global_atomic_add_f32 v252, v2, s[8:9]
	s_mov_b64 exec, -1
	v_add_u32_e32 v164, 0x10000, v164
	v_add_u32_e32 v165, 0x8000, v165
	v_mov_b32_e32 v2, 0
	v_mov_b32_e32 v3, 0
	s_waitcnt vmcnt(18)
	v_pk_fma_f32 v[68:69], v[16:17], v[72:73], v[68:69]
	v_pk_fma_f32 v[70:71], v[18:19], v[74:75], v[70:71]
	v_pk_fma_f32 v[52:53], v[12:13], v[76:77], v[52:53]
	v_pk_fma_f32 v[54:55], v[14:15], v[78:79], v[54:55]
	global_store_dwordx4 v164, v[68:71], s[2:3] offset:0
	global_store_dwordx4 v164, v[52:55], s[2:3] offset:64
	v_pk_fma_f32 v[2:3], v[68:69], v[68:69], v[2:3]
	v_pk_fma_f32 v[2:3], v[70:71], v[70:71], v[2:3]
	v_pk_fma_f32 v[2:3], v[52:53], v[52:53], v[2:3]
	v_pk_fma_f32 v[2:3], v[54:55], v[54:55], v[2:3]
	v_pk_mul_f32 v[252:253], v[68:69], v[170:171]
	v_cvt_pk_bf16_f32 v176, v252, v253
	v_pk_mul_f32 v[252:253], v[70:71], v[172:173]
	v_cvt_pk_bf16_f32 v177, v252, v253
	v_pk_mul_f32 v[252:253], v[52:53], v[166:167]
	v_cvt_pk_bf16_f32 v178, v252, v253
	v_pk_mul_f32 v[252:253], v[54:55], v[168:169]
	v_cvt_pk_bf16_f32 v179, v252, v253
	s_nop 1
	v_permlane16_swap_b32_e32 v176, v178
	v_permlane16_swap_b32_e32 v177, v179
	global_store_dwordx4 v165, v[176:179], s[92:93] offset:0
	s_waitcnt vmcnt(15)
	v_pk_fma_f32 v[48:49], v[8:9], v[60:61], v[48:49]
	v_pk_fma_f32 v[50:51], v[10:11], v[62:63], v[50:51]
	v_pk_fma_f32 v[44:45], v[4:5], v[56:57], v[44:45]
	v_pk_fma_f32 v[46:47], v[6:7], v[58:59], v[46:47]
	global_store_dwordx4 v164, v[48:51], s[2:3] offset:512
	global_store_dwordx4 v164, v[44:47], s[2:3] offset:576
	v_pk_fma_f32 v[2:3], v[48:49], v[48:49], v[2:3]
	v_pk_fma_f32 v[2:3], v[50:51], v[50:51], v[2:3]
	v_pk_fma_f32 v[2:3], v[44:45], v[44:45], v[2:3]
	v_pk_fma_f32 v[2:3], v[46:47], v[46:47], v[2:3]
	v_pk_mul_f32 v[252:253], v[48:49], v[160:161]
	v_cvt_pk_bf16_f32 v176, v252, v253
	v_pk_mul_f32 v[252:253], v[50:51], v[162:163]
	v_cvt_pk_bf16_f32 v177, v252, v253
	v_pk_mul_f32 v[252:253], v[44:45], v[156:157]
	v_cvt_pk_bf16_f32 v178, v252, v253
	v_pk_mul_f32 v[252:253], v[46:47], v[158:159]
	v_cvt_pk_bf16_f32 v179, v252, v253
	s_nop 1
	v_permlane16_swap_b32_e32 v176, v178
	v_permlane16_swap_b32_e32 v177, v179
	global_store_dwordx4 v165, v[176:179], s[92:93] offset:256
	v_add_f32_e32 v2, v2, v3
	v_mov_b32_e32 v0, v2
	s_nop 1
	v_permlane16_swap_b32_e32 v2, v0
	v_add_f32_e32 v2, v2, v0
	v_mov_b32_e32 v0, v2
	s_nop 1
	v_permlane32_swap_b32_e32 v2, v0
	v_add_f32_e32 v2, v2, v0
	v_lshrrev_b32_e32 v252, 12, v164
	v_lshlrev_b32_e32 v252, 2, v252
	s_mov_b64 exec, 0xffff
	global_atomic_add_f32 v252, v2, s[8:9]
	s_mov_b64 exec, -1
	s_branch .LBB0_823
